# F1: wide gate loads issued at the last prefetching K-iteration (counted waits skip them) on top of v089
# speedup vs baseline: 1.0036x; 1.0036x over previous
.LBB0_166:
	s_andn2_b64 vcc, exec, s[4:5]
	s_cbranch_vccnz .LBB0_168
	s_add_i32 s4, s18, 0xffff4000
	s_cmp_lg_u32 s15, 0
	s_cselect_b32 s17, s4, 0x18000
	s_lshl_b64 s[4:5], s[0:1], 1
	s_add_i32 s17, s13, s17
	v_lshl_add_u64 v[196:197], v[178:179], 0, s[4:5]
	s_mov_b32 m0, s17
	s_nop 0
	global_load_lds_dwordx4 v[196:197], off
	v_lshl_add_u64 v[196:197], v[180:181], 0, s[4:5]
	s_add_i32 m0, s17, 0x2000
	s_nop 0
	global_load_lds_dwordx4 v[196:197], off
	v_lshl_add_u64 v[196:197], v[182:183], 0, s[4:5]
	s_add_i32 m0, s17, 0x4000
	s_nop 0
	global_load_lds_dwordx4 v[196:197], off
	v_lshl_add_u64 v[196:197], v[184:185], 0, s[4:5]
	s_add_i32 m0, s17, 0x6000
	s_nop 0
	global_load_lds_dwordx4 v[196:197], off
	v_lshl_add_u64 v[196:197], v[186:187], 0, s[4:5]
	s_add_i32 m0, s17, 0x8000
	s_nop 0
	global_load_lds_dwordx4 v[196:197], off
	v_lshl_add_u64 v[196:197], v[190:191], 0, s[4:5]
	s_add_i32 m0, s17, 0xa000
	s_mov_b32 s17, s18
	global_load_lds_dwordx4 v[196:197], off
	s_add_i32 vcc_lo, s16, 3
	s_cmp_lg_u32 vcc_lo, s12
	s_cbranch_scc1 .Lf1g_skip
	s_lshl_b32 vcc_lo, s11, 11
	s_add_u32 vcc_lo, s94, vcc_lo
	s_addc_u32 vcc_hi, s95, 0
	v_lshrrev_b32_e32 v250, 1, v204
	v_and_b32_e32 v250, 24, v250
	v_mov_b32_e32 v251, v189
	v_lshl_add_u64 v[250:251], v[66:67], 0, v[250:251]
	v_lshl_add_u64 v[196:197], vcc, 0, v[94:95]
	v_lshl_add_u64 v[196:197], v[196:197], 0, v[250:251]
	global_load_dwordx4 v[174:177], v[196:197], off
	global_load_dwordx4 v[170:173], v[196:197], off offset:64
	v_lshl_add_u64 v[196:197], vcc, 0, v[114:115]
	v_lshl_add_u64 v[196:197], v[196:197], 0, v[250:251]
	global_load_dwordx4 v[166:169], v[196:197], off
	global_load_dwordx4 v[162:165], v[196:197], off offset:64
	v_lshl_add_u64 v[196:197], vcc, 0, v[126:127]
	v_lshl_add_u64 v[196:197], v[196:197], 0, v[250:251]
	global_load_dwordx4 v[158:161], v[196:197], off
	global_load_dwordx4 v[154:157], v[196:197], off offset:64
	v_lshl_add_u64 v[196:197], vcc, 0, v[128:129]
	v_lshl_add_u64 v[196:197], v[196:197], 0, v[250:251]
	global_load_dwordx4 v[150:153], v[196:197], off
	global_load_dwordx4 v[146:149], v[196:197], off offset:64
.Lf1g_skip:
.LBB0_168:
	s_add_i32 s4, s17, 0
	s_add_i32 s5, s4, s14
	v_add_u32_e32 v206, s5, v194
	v_add_u32_e32 v215, v206, v188
	v_add_u32_e32 v228, s4, v193
	v_add_u32_e32 v229, v228, v188
	ds_read_b128 v[200:203], v229
	ds_read_b128 v[196:199], v215 offset:32768
	ds_read_b128 v[216:219], v215 offset:34816
	ds_read_b128 v[220:223], v215 offset:36864
	ds_read_b128 v[224:227], v215 offset:38912
	ds_read_b128 v[246:249], v229 offset:2048
	v_add_u32_e32 v206, v206, v195
	v_add_u32_e32 v228, v228, v195
	s_waitcnt lgkmcnt(4)
	v_mfma_f32_16x16x32_bf16 v[60:63], v[196:199], v[200:203], v[60:63]
	s_waitcnt lgkmcnt(3)
	v_mfma_f32_16x16x32_bf16 v[56:59], v[216:219], v[200:203], v[56:59]
	s_waitcnt lgkmcnt(2)
	v_mfma_f32_16x16x32_bf16 v[52:55], v[220:223], v[200:203], v[52:55]
	s_waitcnt lgkmcnt(1)
	v_mfma_f32_16x16x32_bf16 v[48:51], v[224:227], v[200:203], v[48:51]
	ds_read_b128 v[200:203], v229 offset:4096
	ds_read_b128 v[230:233], v206 offset:32768
	ds_read_b128 v[234:237], v206 offset:34816
	s_waitcnt lgkmcnt(3)
	v_mfma_f32_16x16x32_bf16 v[44:47], v[196:199], v[246:249], v[44:47]
	v_mfma_f32_16x16x32_bf16 v[40:43], v[216:219], v[246:249], v[40:43]
	v_mfma_f32_16x16x32_bf16 v[36:39], v[220:223], v[246:249], v[36:39]
	v_mfma_f32_16x16x32_bf16 v[32:35], v[224:227], v[246:249], v[32:35]
	ds_read_b128 v[246:249], v229 offset:6144
	ds_read_b128 v[238:241], v206 offset:36864
	ds_read_b128 v[242:245], v206 offset:38912
	s_waitcnt lgkmcnt(5)
	v_mfma_f32_16x16x32_bf16 v[28:31], v[196:199], v[200:203], v[28:31]
	v_mfma_f32_16x16x32_bf16 v[24:27], v[216:219], v[200:203], v[24:27]
	v_mfma_f32_16x16x32_bf16 v[20:23], v[220:223], v[200:203], v[20:23]
	v_mfma_f32_16x16x32_bf16 v[16:19], v[224:227], v[200:203], v[16:19]
	ds_read_b128 v[200:203], v228
	s_waitcnt lgkmcnt(3)
	v_mfma_f32_16x16x32_bf16 v[12:15], v[196:199], v[246:249], v[12:15]
	v_mfma_f32_16x16x32_bf16 v[8:11], v[216:219], v[246:249], v[8:11]
	v_mfma_f32_16x16x32_bf16 v[4:7], v[220:223], v[246:249], v[4:7]
	v_mfma_f32_16x16x32_bf16 v[0:3], v[224:227], v[246:249], v[0:3]
	ds_read_b128 v[246:249], v228 offset:2048
	s_waitcnt lgkmcnt(1)
	v_mfma_f32_16x16x32_bf16 v[60:63], v[230:233], v[200:203], v[60:63]
	v_mfma_f32_16x16x32_bf16 v[56:59], v[234:237], v[200:203], v[56:59]
	v_mfma_f32_16x16x32_bf16 v[52:55], v[238:241], v[200:203], v[52:55]
	v_mfma_f32_16x16x32_bf16 v[48:51], v[242:245], v[200:203], v[48:51]
	ds_read_b128 v[200:203], v228 offset:4096
	s_waitcnt lgkmcnt(1)
	v_mfma_f32_16x16x32_bf16 v[44:47], v[230:233], v[246:249], v[44:47]
	v_mfma_f32_16x16x32_bf16 v[40:43], v[234:237], v[246:249], v[40:43]
	v_mfma_f32_16x16x32_bf16 v[36:39], v[238:241], v[246:249], v[36:39]
	v_mfma_f32_16x16x32_bf16 v[32:35], v[242:245], v[246:249], v[32:35]
	ds_read_b128 v[246:249], v228 offset:6144
	s_waitcnt lgkmcnt(1)
	v_mfma_f32_16x16x32_bf16 v[28:31], v[230:233], v[200:203], v[28:31]
	v_mfma_f32_16x16x32_bf16 v[24:27], v[234:237], v[200:203], v[24:27]
	v_mfma_f32_16x16x32_bf16 v[20:23], v[238:241], v[200:203], v[20:23]
	v_mfma_f32_16x16x32_bf16 v[16:19], v[242:245], v[200:203], v[16:19]
	s_waitcnt lgkmcnt(0)
	v_mfma_f32_16x16x32_bf16 v[12:15], v[230:233], v[246:249], v[12:15]
	v_mfma_f32_16x16x32_bf16 v[8:11], v[234:237], v[246:249], v[8:11]
	v_mfma_f32_16x16x32_bf16 v[4:7], v[238:241], v[246:249], v[4:7]
	v_mfma_f32_16x16x32_bf16 v[0:3], v[242:245], v[246:249], v[0:3]
	s_mov_b64 s[4:5], -1
	s_and_b64 vcc, exec, s[2:3]
	s_cbranch_vccz .LBB0_170
	s_waitcnt vmcnt(8)
	s_waitcnt lgkmcnt(0)
	s_barrier
	s_mov_b64 s[4:5], 0
.LBB0_170:
	s_andn2_b64 vcc, exec, s[4:5]
	s_cbranch_vccnz .LBB0_163
	s_add_i32 vcc_lo, s16, 3
	s_cmp_lg_u32 vcc_lo, s12
	s_cbranch_scc1 .Lf1g_w6
	s_waitcnt vmcnt(14)
	s_branch .Lf1g_wd
